# windowed attention: sink-logit load issued in the unit prologue instead of load-then-wait in the epilogue (epilogue de-serialisation)
# baseline (speedup 1.0000x reference)
; DI float shx_(int lane, float v, int m) { return __builtin_bit_cast(float, __builtin_amdgcn_ds_bpermute((lane ^ m) << 2, __builtin_bit_cast(int, v))); }
; DI unsigned pkbf(float a, float b) { fv2 v = {a, b}; return __builtin_bit_cast(unsigned, __builtin_convertvector(v, bfv2)); }
; DI void win_mfma_phase(const Args& A, int wave_s, int l, bool need_ctx, LAS unsigned char* lds) {
;     ...
;         ls += shx_(C.lane, ls, 32);
;         const float inv = 1.f / (ls + __builtin_amdgcn_exp2f(C.wsink[l * 8 + head] * 1.4426950408889634f - Mb2));
;         bf16* op = C.MIX + (size_t)(qrow0 + qh * 32 + r) * 1024 + head * 64;
; #pragma unroll
;         for (int mt = 0; mt < 2; ++mt)
; #pragma unroll
;             for (int gg = 0; gg < 4; ++gg) { const int dv0 = 32 * mt + 8 * gg + 4 * h;
;                 v2u w; w.x = pkbf(O[mt][4 * gg] * inv, O[mt][4 * gg + 1] * inv); w.y = pkbf(O[mt][4 * gg + 2] * inv, O[mt][4 * gg + 3] * inv);
;                 *(v2u*)(op + dv0) = w; }
.LBB0_306:
	s_add_i32 s96, s7, s8
	v_readlane_b32 s12, v252, 1
	s_lshl_b64 s[4:5], s[96:97], 2
	v_readlane_b32 s18, v252, 7
	v_readlane_b32 s19, v252, 8
	s_add_u32 s4, s18, s4
	s_addc_u32 s5, s19, s5
	s_nop 0
	ds_bpermute_b32 v1, v117, v132
	s_mov_b32 s4, 0x3fb8aa3b
	s_lshl_b32 s96, s11, 1
	s_add_i32 s9, s9, s90
	s_cmp_ge_i32 s9, s2
	s_waitcnt lgkmcnt(0)
	v_add_f32_e32 v1, v132, v1
	v_readlane_b32 s13, v252, 2
	v_readlane_b32 s14, v252, 3
	v_readlane_b32 s15, v252, 4
	v_readlane_b32 s16, v252, 5
	v_readlane_b32 s17, v252, 6
	v_readlane_b32 s20, v252, 9
	v_readlane_b32 s21, v252, 10
	v_readlane_b32 s22, v252, 11
	v_readlane_b32 s23, v252, 12
	v_readlane_b32 s24, v252, 13
	v_readlane_b32 s25, v252, 14
	v_readlane_b32 s26, v252, 15
	v_readlane_b32 s27, v252, 16
	s_waitcnt vmcnt(0)
	v_mov_b32_e32 v2, v164
	v_fma_f32 v2, v2, s4, -v124
	v_exp_f32_e32 v2, v2
	s_nop 0
	v_add_f32_e32 v1, v1, v2
	v_div_scale_f32 v2, s[4:5], v1, v1, 1.0
	v_rcp_f32_e32 v3, v2
	v_readlane_b32 s4, v253, 62
	v_readlane_b32 s5, v253, 63
	v_fma_f32 v4, -v2, v3, 1.0
	v_fmac_f32_e32 v3, v4, v3
	v_div_scale_f32 v4, vcc, 1.0, v1, 1.0
	v_mul_f32_e32 v5, v4, v3
	v_fma_f32 v6, -v2, v5, v4
	v_fmac_f32_e32 v5, v6, v3
	v_fma_f32 v2, -v2, v5, v4
	v_div_fmas_f32 v2, v2, v3, v5
	v_lshlrev_b64 v[4:5], 11, v[120:121]
	v_div_fixup_f32 v2, v2, v1, 1.0
	v_lshl_add_u64 v[4:5], s[4:5], 0, v[4:5]
	v_lshl_add_u64 v[4:5], v[4:5], 0, s[96:97]
	v_pk_mul_f32 v[6:7], v[48:49], v[2:3] op_sel_hi:[1,0]
	v_pk_mul_f32 v[8:9], v[50:51], v[2:3] op_sel_hi:[1,0]
	v_cvt_pk_bf16_f32 v6, v6, v7
	v_cvt_pk_bf16_f32 v7, v8, v9
	v_lshl_add_u64 v[4:5], v[112:113], 1, v[4:5]
	global_store_dwordx2 v[4:5], v[6:7], off
	v_pk_mul_f32 v[6:7], v[52:53], v[2:3] op_sel_hi:[1,0]
	v_pk_mul_f32 v[8:9], v[54:55], v[2:3] op_sel_hi:[1,0]
	v_cvt_pk_bf16_f32 v6, v6, v7
	v_cvt_pk_bf16_f32 v7, v8, v9
	global_store_dwordx2 v[4:5], v[6:7], off offset:16
	v_pk_mul_f32 v[6:7], v[56:57], v[2:3] op_sel_hi:[1,0]
	v_pk_mul_f32 v[8:9], v[58:59], v[2:3] op_sel_hi:[1,0]
	v_cvt_pk_bf16_f32 v6, v6, v7
	v_cvt_pk_bf16_f32 v7, v8, v9
	global_store_dwordx2 v[4:5], v[6:7], off offset:32
	v_pk_mul_f32 v[6:7], v[60:61], v[2:3] op_sel_hi:[1,0]
	v_pk_mul_f32 v[8:9], v[62:63], v[2:3] op_sel_hi:[1,0]
	v_cvt_pk_bf16_f32 v6, v6, v7
	v_cvt_pk_bf16_f32 v7, v8, v9
	global_store_dwordx2 v[4:5], v[6:7], off offset:48
	v_pk_mul_f32 v[6:7], v[32:33], v[2:3] op_sel_hi:[1,0]
	v_pk_mul_f32 v[8:9], v[34:35], v[2:3] op_sel_hi:[1,0]
	v_cvt_pk_bf16_f32 v6, v6, v7
	v_cvt_pk_bf16_f32 v7, v8, v9
	global_store_dwordx2 v[4:5], v[6:7], off offset:64
	v_pk_mul_f32 v[6:7], v[36:37], v[2:3] op_sel_hi:[1,0]
	v_pk_mul_f32 v[8:9], v[38:39], v[2:3] op_sel_hi:[1,0]
	v_cvt_pk_bf16_f32 v6, v6, v7
	v_cvt_pk_bf16_f32 v7, v8, v9
	global_store_dwordx2 v[4:5], v[6:7], off offset:80
	v_pk_mul_f32 v[6:7], v[40:41], v[2:3] op_sel_hi:[1,0]
	v_pk_mul_f32 v[8:9], v[42:43], v[2:3] op_sel_hi:[1,0]
	v_cvt_pk_bf16_f32 v6, v6, v7
	v_cvt_pk_bf16_f32 v7, v8, v9
	global_store_dwordx2 v[4:5], v[6:7], off offset:96
	v_pk_mul_f32 v[6:7], v[44:45], v[2:3] op_sel_hi:[1,0]
	v_pk_mul_f32 v[2:3], v[46:47], v[2:3] op_sel_hi:[1,0]
	v_cvt_pk_bf16_f32 v6, v6, v7
	v_cvt_pk_bf16_f32 v7, v2, v3
	global_store_dwordx2 v[4:5], v[6:7], off offset:112
	s_cbranch_scc1 .LBB0_325

; #define LAS __attribute__((address_space(3)))
; DI void win_mfma_phase(const Args& A, int wave_s, int l, bool need_ctx, LAS unsigned char* lds) {
;     ...
;         const bf16* qp = C.P + (size_t)(qrow0 + qh * 32 + r) * INW + CA_Q + head * 64;
;         bf16x8 Qf[4];
; #pragma unroll
;         for (int s = 0; s < 4; ++s) Qf[s] = *(const bf16x8*)(qp + s * 16 + h * 8);
;         f32x16 O[2];
; #pragma unroll
;         for (int mt = 0; mt < 2; ++mt)
; #pragma unroll
;             for (int i = 0; i < 16; ++i) O[mt][i] = 0.f;
;         float ls = 0.f;
;         v4u kreg, vreg, kreg2, vreg2;
;         auto tile_row = [&](int it) -> int { return it < nloc ? b * LSEQ + t0 + 64 * (tfirst + it - 2) : NLAT + b * LCTX + 64 * (it - nloc); };
;         { const bf16* kr = C.P + (size_t)(tile_row(0) + srow) * INW; kreg = *(const v4u*)(kr + CA_K + kv * 64 + sch * 8); vreg = *(const v4u*)(kr + CA_V + kv * 64 + sch * 8); }
;         { const bf16* kr = C.P + (size_t)(tile_row(1) + srow) * INW; kreg2 = *(const v4u*)(kr + CA_K + kv * 64 + sch * 8); vreg2 = *(const v4u*)(kr + CA_V + kv * 64 + sch * 8); }
;         __syncthreads();
;         *(LAS v4u*)(lds + srow * KV_PITCH + sch * 16) = kreg; *(LAS v4u*)(lds + 2 * KV_IMG + srow * KV_PITCH + sch * 16) = vreg;
;         kreg = kreg2; vreg = vreg2;
;         __syncthreads();
;     ...
;         const float inv = 1.f / (ls + __builtin_amdgcn_exp2f(C.wsink[l * 8 + head] * 1.4426950408889634f - Mb2));
.LBB0_319:
	s_lshl_b32 s11, s12, 6
	v_add_u32_e32 v1, s17, v125
	v_mov_b64_e32 v[10:11], s[84:85]
	v_mad_i64_i32 v[10:11], s[4:5], v1, s77, v[10:11]
	s_lshl_b32 s96, s11, 1
	v_lshl_add_u64 v[10:11], v[10:11], 0, s[96:97]
	v_lshl_add_u64 v[10:11], v[10:11], 0, v[160:161]
	global_load_dwordx4 v[100:103], v[10:11], off offset:1024
	global_load_dwordx4 v[96:99], v[10:11], off offset:1280
	s_add_i32 s4, s14, s15
	v_mov_b32_e32 v132, 0
	v_ashrrev_i32_e32 v121, 31, v120
	s_lshl_b32 s11, s7, 6
	s_add_i32 s12, s10, 4
	s_add_i32 s13, s13, 0x8000
	s_mov_b32 s14, 0
	s_sub_i32 s15, 0, s10
	v_subrev_u32_e32 v131, s16, v130
	v_mov_b32_e32 v48, 0
	v_mov_b32_e32 v32, 0
	s_add_i32 s16, s4, 0xffffff80
	v_mov_b32_e32 v49, v132
	v_mov_b32_e32 v50, v132
	v_mov_b32_e32 v51, v132
	v_mov_b32_e32 v52, v132
	v_mov_b32_e32 v53, v132
	v_mov_b32_e32 v54, v132
	v_mov_b32_e32 v55, v132
	v_mov_b32_e32 v56, v132
	v_mov_b32_e32 v57, v132
	v_mov_b32_e32 v58, v132
	v_mov_b32_e32 v59, v132
	v_mov_b32_e32 v60, v132
	v_mov_b32_e32 v61, v132
	v_mov_b32_e32 v62, v132
	v_mov_b32_e32 v63, v132
	v_mov_b32_e32 v33, v132
	v_mov_b32_e32 v34, v132
	v_mov_b32_e32 v35, v132
	v_mov_b32_e32 v36, v132
	v_mov_b32_e32 v37, v132
	v_mov_b32_e32 v38, v132
	v_mov_b32_e32 v39, v132
	v_mov_b32_e32 v40, v132
	v_mov_b32_e32 v41, v132
	v_mov_b32_e32 v42, v132
	v_mov_b32_e32 v43, v132
	v_mov_b32_e32 v44, v132
	v_mov_b32_e32 v45, v132
	v_mov_b32_e32 v46, v132
	v_lshl_add_u64 v[122:123], v[118:119], 0, s[96:97]
	v_mov_b32_e32 v47, v132
	s_barrier
	s_waitcnt vmcnt(3)
	ds_write_b128 v127, v[2:5]
	s_waitcnt vmcnt(2)
	ds_write_b128 v127, v[6:9] offset:18432
	s_waitcnt lgkmcnt(0)
	s_barrier
	s_add_i32 s96, s7, s8
	s_lshl_b64 s[4:5], s[96:97], 2
	v_readlane_b32 s18, v252, 7
	v_readlane_b32 s19, v252, 8
	s_nop 1
	s_add_u32 s4, s18, s4
	s_addc_u32 s5, s19, s5
	global_load_dword v164, v161, s[4:5]
	s_branch .LBB0_321
